# G4 static re-balancing: the 32 long KVX units (memory-token K/V projection, 32 K-tiles each) run on workgroups G-32..G-1 (least loaded in the phase) instead of 0..31 (most loaded); first-unit pm/pn re
# baseline (speedup 1.0000x reference)
; #define PG8_STAGE(bufoff, gbase, voff) do { _Pragma("unroll") for (int _i = 0; _i < 2; ++_i) \
;         __builtin_amdgcn_global_load_lds((const unsigned*)((const char*)(gbase) + (voff)[_i]), (PG8_LAS unsigned*)(lds + (bufoff) + ldsw + _i * 8192), 16, 0, 0); } while (0)
; #define PG8_WAIT_V(n) asm volatile("s_waitcnt vmcnt(" #n ")" ::: "memory")
; #define PG8_BAR __builtin_amdgcn_s_barrier()
;     __host__ __device__ bool next(int i, Unit& u) const {
;         const long L = (long)i * G + c; if (L >= nwg) return false;
;         int wgid = (int)L; { const int q = nwg / NXCD, r = nwg % NXCD, xcd = wgid % NXCD, off = wgid / NXCD; wgid = (xcd < r ? xcd * (q + 1) : r * (q + 1) + (xcd - r) * q) + off; }
;         const int nig = WGM * nN, gid = wgid / nig, fm = gid * WGM, gsz = (nM - fm) < WGM ? (nM - fm) : WGM;
;         u.pm = fm + ((wgid % nig) % gsz); u.pn = (wgid % nig) / gsz; return true;
;     }
; template <class Epi, class Sched, bool ALIGN_EPI = false, bool SP2 = false>
; __device__ __forceinline__ void gemm_phase(PG8_LAS unsigned char* lds, const Gemm g, const Sched& S, const Epi& E, int wave_id) {
;     ...
;     const char* cA = (const char*)g.A + (size_t)cur.pm * tstep + PG8_KOFF(cur.pn); const char* cB = (const char*)g.Bt + (size_t)cur.pn * tstep + PG8_KOFF(cur.pn);
;     S.a_ready(cur);
;     if constexpr (SP2) {
;         PG8_STAGE(PG8_SB(0, 0), cB, voffB); PG8_STAGE(PG8_SB(0, 1), cB + hstep, voffB); PG8_STAGE(PG8_SA(0, 0), cA, voffA); PG8_STAGE(PG8_SA(0, 1), cA + hstep, voffA);
;         if (wr == 1) PG8_BAR;
;         PG8_WAIT_V(2); PG8_BAR;
;         PG8_STAGE(PG8_SB(1, 0), cB + kstep, voffB); PG8_STAGE(PG8_SA(1, 0), cA + kstep, voffA); PG8_STAGE(PG8_SB(1, 1), cB + hstep + kstep, voffB);
;         PG8_WAIT_V(6); PG8_BAR;
;     } else {
;         PG8_STAGE(PG8_SB(0, 0), cB, voffB); PG8_STAGE(PG8_SA(0, 0), cA, voffA); PG8_STAGE(PG8_SB(0, 1), cB + hstep, voffB); PG8_STAGE(PG8_SA(0, 1), cA + hstep, voffA);
;         if (wr == 1) PG8_BAR;
;         PG8_WAIT_V(4); PG8_BAR;
;         PG8_STAGE(PG8_SB(1, 0), cB + kstep, voffB); PG8_STAGE(PG8_SA(1, 0), cA + kstep, voffA); PG8_STAGE(PG8_SB(1, 1), cB + hstep + kstep, voffB);
;         PG8_WAIT_V(6); PG8_BAR;
.LBB0_700:
	s_not_b32 s38, s2
	v_mbcnt_lo_u32_b32 v0, -1, 0
	v_mbcnt_hi_u32_b32 v0, -1, v0
	s_add_i32 s38, s38, s3
	v_add_u32_e32 v8, s29, v0
	s_and_b32 s39, s38, 7
	s_lshl_b32 s39, s39, 2
	s_lshr_b32 s32, s38, 3
	s_add_i32 s32, s32, s39
	s_cmp_gt_u32 s38, 31
	v_readfirstlane_b32 s50, v8
	s_cbranch_scc1 .LBB0_758
	v_lshlrev_b32_e32 v0, 4, v8
	v_add_u32_e32 v1, 0x2000, v0
	s_waitcnt vmcnt(0)
	v_ashrrev_i32_e32 v2, 31, v1
	v_lshrrev_b32_e32 v2, 22, v2
	v_add_u32_e32 v2, v1, v2
	v_ashrrev_i32_e32 v9, 10, v2
	v_mul_i32_i24_e32 v2, 0x400, v9
	v_sub_u32_e32 v1, v1, v2
	v_lshrrev_b32_e32 v2, 4, v1
	v_bitop3_b32 v1, v2, v1, 32 bitop3:0x6c
	v_ashrrev_i32_e32 v2, 31, v1
	v_lshrrev_b32_e32 v2, 26, v2
	v_add_u32_e32 v2, v1, v2
	v_lshlrev_b32_e32 v3, 3, v9
	v_ashrrev_i32_e32 v10, 6, v2
	v_and_b32_e32 v3, -16, v3
	v_add_u32_e32 v3, v10, v3
	v_and_b32_e32 v4, 3, v10
	s_mov_b32 s38, 0xfffe0
	v_lshrrev_b32_e32 v5, 2, v3
	v_lshlrev_b32_e32 v6, 1, v3
	v_and_or_b32 v4, v3, s38, v4
	v_and_b32_e32 v5, 4, v5
	v_and_b32_e32 v6, 24, v6
	v_and_b32_e32 v2, 0xc0, v2
	v_or3_b32 v4, v4, v5, v6
	v_sub_u32_e32 v1, v1, v2
	v_mov_b32_e32 v6, 1
	v_lshlrev_b32_e32 v5, 5, v9
	v_ashrrev_i16_sdwa v1, v6, sext(v1) dst_sel:DWORD dst_unused:UNUSED_PAD src0_sel:DWORD src1_sel:BYTE_0
	v_and_b32_e32 v5, 32, v5
	v_bfe_i32 v11, v1, 0, 16
	v_add_lshl_u32 v1, v5, v11, 1
	v_lshl_add_u32 v128, v4, 12, v1
	v_lshl_add_u32 v130, v3, 12, v1
	v_bfe_i32 v1, v8, 27, 1
	v_lshrrev_b32_e32 v1, 22, v1
	v_add_u32_e32 v1, v0, v1
	v_and_b32_e32 v1, 0xfffffc00, v1
	v_sub_u32_e32 v0, v0, v1
	v_lshrrev_b32_e32 v1, 4, v0
	v_ashrrev_i32_e32 v2, 31, v8
	v_bitop3_b32 v0, v1, v0, 32 bitop3:0x6c
	v_lshrrev_b32_e32 v2, 26, v2
	v_ashrrev_i32_e32 v1, 31, v0
	v_add_u32_e32 v2, v8, v2
	v_lshrrev_b32_e32 v1, 26, v1
	v_ashrrev_i32_e32 v13, 6, v2
	v_add_u32_e32 v1, v0, v1
	v_lshlrev_b32_e32 v2, 3, v13
	s_waitcnt lgkmcnt(0)
	s_add_u32 s29, s48, 0x300000
	v_ashrrev_i32_e32 v12, 6, v1
	v_and_b32_e32 v2, -16, v2
	s_addc_u32 s68, s49, 0
	v_add_u32_e32 v2, v12, v2
	s_add_u32 s69, s48, 0x8500000
	v_and_b32_e32 v3, 3, v12
	v_lshrrev_b32_e32 v4, 2, v2
	v_lshlrev_b32_e32 v5, 1, v2
	v_and_b32_e32 v1, 0xc0, v1
	s_addc_u32 s70, s49, 0
	s_ashr_i32 s52, s50, 6
	v_and_or_b32 v3, v2, s38, v3
	v_and_b32_e32 v4, 4, v4
	v_and_b32_e32 v5, 24, v5
	v_sub_u32_e32 v0, v0, v1
	s_ashr_i32 s51, s50, 8
	s_lshl_b32 s71, s52, 10
	v_or3_b32 v3, v3, v4, v5
	v_lshlrev_b32_e32 v4, 5, v13
	v_ashrrev_i16_sdwa v0, v6, sext(v0) dst_sel:DWORD dst_unused:UNUSED_PAD src0_sel:DWORD src1_sel:BYTE_0
	s_lshr_b32 s38, s32, 3
	s_lshl_b32 s38, s38, 20
	s_mov_b32 s39, 0
	v_and_b32_e32 v4, 32, v4
	v_bfe_i32 v14, v0, 0, 16
	s_nop 0
	s_add_u32 s62, s69, s38
	v_add_lshl_u32 v0, v4, v14, 1
	s_addc_u32 s63, s70, s39
	s_add_i32 s72, s71, 0
	v_lshl_add_u32 v194, v3, 12, v0
	s_add_i32 m0, s72, 0x10000
	s_and_b32 s38, s32, 7
	s_lshl_b32 s38, s38, 20
	s_mov_b32 s39, 0
	global_load_lds_dwordx4 v194, s[62:63]
	s_add_i32 m0, s72, 0x12000
	s_nop 0
	s_add_u32 s42, s29, s38
	s_addc_u32 s43, s68, s39
	s_add_u32 s38, s62, 0x80000
	global_load_lds_dwordx4 v128, s[62:63]
	s_addc_u32 s39, s63, 0
	s_add_i32 m0, s72, 0x14000
	s_add_i32 s73, s72, 0x2000
	global_load_lds_dwordx4 v194, s[38:39]
	s_add_i32 m0, s72, 0x16000
	v_lshl_add_u32 v132, v2, 12, v0
	global_load_lds_dwordx4 v128, s[38:39]
	s_mov_b32 m0, s72
	s_add_u32 s38, s42, 0x80000
	global_load_lds_dwordx4 v132, s[42:43]
	s_mov_b32 m0, s73
	s_addc_u32 s39, s43, 0
	s_add_i32 s74, s72, 0x4000
	global_load_lds_dwordx4 v130, s[42:43]
	s_mov_b32 m0, s74
	s_add_i32 s75, s72, 0x6000
	global_load_lds_dwordx4 v132, s[38:39]
	s_mov_b32 m0, s75
	v_mov_b32_e32 v129, v195
	global_load_lds_dwordx4 v130, s[38:39]
	v_mov_b32_e32 v133, v195
	v_mov_b32_e32 v131, v195
	s_cmp_eq_u32 s51, 1
	v_lshl_add_u64 v[6:7], s[62:63], 0, v[194:195]
	v_lshl_add_u64 v[4:5], s[62:63], 0, v[128:129]
	v_lshl_add_u64 v[0:1], s[42:43], 0, v[132:133]
	s_cselect_b64 s[44:45], -1, 0
	s_cmp_lg_u32 s51, 1
	v_lshl_add_u64 v[2:3], s[42:43], 0, v[130:131]
	s_cbranch_scc1 .LBB0_703
	s_barrier
.LBB0_703:
	s_add_u32 s48, s48, 0xb00000
	s_addc_u32 s49, s49, 0
	s_lshl_b32 s38, s52, 5
	s_and_b32 s41, s38, 0x60
	s_add_i32 m0, s72, 0x18000
	v_lshl_add_u64 v[6:7], v[6:7], 0, s[14:15]
	s_lshl_b32 s40, s51, 13
	s_lshl_b32 s52, s41, 7
	s_waitcnt vmcnt(2)
	s_barrier
	global_load_lds_dwordx4 v[6:7], off
	v_lshl_add_u64 v[4:5], v[4:5], 0, s[14:15]
	s_add_i32 m0, s72, 0x1a000
	s_add_i32 s76, s72, 0x8000
	s_add_i32 s77, s72, 0xa000
	global_load_lds_dwordx4 v[4:5], off
	v_lshl_add_u64 v[0:1], v[0:1], 0, s[14:15]
	s_mov_b32 m0, s76
	s_add_u32 s38, s62, 0x80080
	global_load_lds_dwordx4 v[0:1], off
	v_lshl_add_u64 v[0:1], v[2:3], 0, s[14:15]
	s_mov_b32 m0, s77
	s_addc_u32 s39, s63, 0
	global_load_lds_dwordx4 v[0:1], off
	s_add_i32 m0, s72, 0x1c000
	v_lshl_add_u64 v[0:1], s[38:39], 0, v[194:195]
	global_load_lds_dwordx4 v[0:1], off
	v_lshl_add_u64 v[0:1], s[38:39], 0, v[128:129]
	s_add_i32 m0, s72, 0x1e000
	s_cmpk_lt_u32 s50, 0x100
	global_load_lds_dwordx4 v[0:1], off
	v_bfe_u32 v0, v8, 4, 2
	v_and_b32_e32 v1, 15, v8
	v_lshlrev_b32_e32 v2, 4, v0
	v_lshl_or_b32 v144, s51, 6, v1
	v_lshl_or_b32 v1, v1, 6, v2
	v_lshlrev_b32_e32 v2, 2, v8
	v_lshl_or_b32 v146, v0, 3, s41
	v_lshlrev_b32_e32 v0, 15, v13
	v_and_b32_e32 v2, 32, v2
	v_and_b32_e32 v0, 0xffff0000, v0
	v_bitop3_b32 v3, v1, s40, v2 bitop3:0xde
	v_bitop3_b32 v145, v1, s52, v2 bitop3:0xde
	v_lshl_add_u32 v0, v12, 12, v0
	v_and_b32_e32 v1, 1, v13
	v_lshl_or_b32 v0, v1, 6, v0
	v_lshl_add_u32 v134, v14, 1, v0
	v_lshlrev_b32_e32 v0, 15, v9
	v_and_b32_e32 v0, 0xffff0000, v0
	s_waitcnt vmcnt(6)
	v_lshl_add_u32 v0, v10, 12, v0
	v_and_b32_e32 v1, 1, v9
	v_lshl_or_b32 v0, v1, 6, v0
	s_nop 0
	s_cselect_b64 s[50:51], -1, 0
	v_mov_b32_e32 v135, v195
	v_lshl_add_u32 v136, v11, 1, v0
	v_mov_b32_e32 v137, v195
	s_mov_b32 s81, 0
	v_add_u32_e32 v147, 0, v3
	s_lshr_b32 s83, s32, 3
	s_and_b32 s82, s32, 7
	s_barrier
	v_readlane_b32 s39, v254, 44
	s_branch .LBB0_706
